# logical CU id := rank-on-XCC*8 + XCC id (census-based, checked 8x32 else fallback); XCD x owns row tiles 6x..6x+5 through out-proj/ff1/ff2; XCD-local barriers (no L2 writeback / cross-XCD round) after
# speedup vs baseline: 1.0088x; 1.0088x over previous
.LBB0_415:
	s_mov_b32 s6, s71
	s_waitcnt vmcnt(0)
	s_barrier
	s_and_saveexec_b64 s[0:1], s[26:27]
	s_cbranch_execz .LBB0_452
	s_add_i32 s8, 0, 0x20020
	v_mov_b32_e32 v0, s8
	s_add_i32 s8, 0, 0x20024
	s_waitcnt vmcnt(0) expcnt(0) lgkmcnt(0)
	ds_read_b32 v2, v0
	v_mov_b32_e32 v0, s8
	ds_read_b32 v0, v0
	s_waitcnt lgkmcnt(0)
	v_cmp_ne_u32_e32 vcc, 32, v2
	v_cmp_ne_u32_e64 s[4:5], 8, v0
	s_or_b64 vcc, vcc, s[4:5]
	s_cmp_gt_u32 s6, 7
	s_cselect_b64 s[4:5], exec, 0
	s_or_b64 vcc, vcc, s[4:5]
	s_and_b64 vcc, vcc, exec
	s_cbranch_vccz .Lmy_cen_ok
	v_readlane_b32 s4, v254, 10
	v_readlane_b32 s5, v254, 11
	v_mov_b32_e32 v3, 0x3800
	v_mov_b32_e32 v4, 1
	s_nop 2
	global_atomic_add v3, v4, s[4:5]
	s_waitcnt vmcnt(0)
.Lmy_cen_ok:
	s_mov_b64 s[4:5], exec
	v_mbcnt_lo_u32_b32 v1, s4, 0
	v_mbcnt_hi_u32_b32 v1, s5, v1
	s_mov_b32 s7, 0
	s_lshl_b32 s22, s6, 6
	v_cmp_eq_u32_e32 vcc, 0, v1
	s_and_saveexec_b64 s[8:9], vcc
	s_cbranch_execz .LBB0_418
	s_add_i32 s6, s22, 0x500
	s_lshl_b64 s[6:7], s[6:7], 2
	v_readlane_b32 s10, v254, 10
	v_readlane_b32 s11, v254, 11
	s_add_u32 s6, s10, s6
	s_addc_u32 s7, s11, s7
	s_bcnt1_i32_b64 s4, s[4:5]
	v_mov_b32_e32 v3, 0
	v_mov_b32_e32 v4, s4
	global_atomic_add v3, v3, v4, s[6:7] sc0

.LBB0_452:
	v_writelane_b32 v254, s78, 13
	s_nop 1
	v_writelane_b32 v254, s79, 14
	v_writelane_b32 v254, s74, 15
	s_nop 1
	v_writelane_b32 v254, s75, 16
	s_or_b64 exec, exec, s[0:1]
	v_readlane_b32 s58, v254, 10
	v_readlane_b32 s59, v254, 11
	v_mov_b32_e32 v0, 0x3800
	s_nop 4
	global_load_dword v0, v0, s[58:59] sc1
	v_cmp_eq_u32_e32 vcc, 0, v228
	s_and_saveexec_b64 s[60:61], vcc
	s_cbranch_execz .Lmy_rank_skip
	v_mov_b32_e32 v1, s71
	v_lshlrev_b32_e32 v1, 7, v1
	v_add_u32_e32 v1, 0x3900, v1
	v_mov_b32_e32 v2, 1
	global_atomic_add v2, v1, v2, s[58:59] sc0
	s_waitcnt vmcnt(0)
	v_mov_b32_e32 v1, 0x20040
	ds_write_b32 v1, v2
.Lmy_rank_skip:
	s_or_b64 exec, exec, s[60:61]
	s_waitcnt vmcnt(0) lgkmcnt(0)
	s_barrier
	v_mov_b32_e32 v1, 0x20040
	ds_read_b32 v1, v1
	v_readfirstlane_b32 s58, v0
	s_waitcnt lgkmcnt(0)
	v_readfirstlane_b32 s59, v1
	s_lshl_b32 s59, s59, 3
	s_add_i32 s59, s59, s71
	s_cmp_eq_u32 s58, 0
	s_cselect_b32 s2, s59, s2
	s_cselect_b32 s58, 1, 0
	s_nop 0
	v_writelane_b32 v255, s58, 46
	s_ashr_i32 s43, s2, 31
	s_lshr_b32 s0, s43, 29
	s_add_i32 s0, s2, s0
	s_and_b32 s1, s0, -8
	s_sub_i32 s1, s2, s1
	s_add_i32 s4, s76, 0xfffffa00
	s_cmp_lt_i32 s1, 0
	s_movk_i32 s7, 0x61
	s_cselect_b32 s5, 45, 44
	s_cselect_b32 s6, 25, 24
	s_cselect_b32 s7, s7, 0x60
	s_cmpk_gt_i32 s42, 0xc0
	s_cselect_b32 s33, s4, s76
	s_add_i32 s4, s42, 0xffffff40
	s_cmpk_gt_i32 s42, 0xc0
	s_cselect_b32 s63, s4, s42
	s_add_i32 s4, s2, 0xffffff40
	s_mov_b32 s8, s76
	s_cmpk_gt_i32 s42, 0xc0
	v_writelane_b32 v254, s8, 17
	s_cselect_b32 s13, s4, s2
	s_cmpk_lt_i32 s2, 0x200
	v_writelane_b32 v254, s9, 18
	s_cselect_b64 s[8:9], -1, 0
	v_writelane_b32 v254, s8, 19
	s_add_i32 s4, s2, 0xa0
	s_bfe_u32 s4, s4, 0x50003
	v_writelane_b32 v254, s9, 20
	s_and_b32 s8, s2, 7
	s_mul_i32 s8, s8, 20
	s_add_i32 s4, s4, s8
	s_mul_i32 s8, s4, 0xcd
	s_bfe_u32 s8, s8, 0x3000d
	s_mul_i32 s9, s8, 40
	s_mul_i32 s5, s5, s1
	s_sub_i32 s9, s4, s9
	s_ashr_i32 s4, s0, 3
	s_add_i32 s5, s5, s4
	s_mul_hi_i32 s0, s5, 0x2e8ba2e9
	s_lshr_b32 s11, s0, 31
	s_ashr_i32 s0, s0, 4
	s_add_i32 s0, s0, s11
	s_mul_i32 s11, s0, 0x58
	s_sub_i32 s5, s5, s11
	s_bfe_i32 s11, s5, 0x80000
	s_bfe_u32 s11, s11, 0x3000c
	s_add_i32 s11, s5, s11
	s_bfe_i32 s12, s11, 0x80000
	s_and_b32 s11, s11, 0xf8
	s_lshl_b32 s8, s8, 2
	s_sub_i32 s5, s5, s11
	s_and_b32 s10, s8, 28
	s_lshl_b32 s0, s0, 3
	s_sext_i32_i8 s5, s5
	s_sub_i32 s10, 16, s10
	s_sext_i32_i16 s12, s12
	s_add_i32 s0, s0, s5
	s_min_u32 s10, s10, 4
	s_ashr_i32 s11, s12, 3
	s_add_i32 s0, s0, 16
	s_ashr_i32 s51, s42, 31
	s_add_u32 s48, s38, 0x4820000
	s_addc_u32 s49, s39, 0
	s_add_u32 s50, s38, 0x3820000
	s_addc_u32 s68, s39, 0
	s_add_u32 s69, s38, 0x5820000
	s_addc_u32 s62, s39, 0
	v_writelane_b32 v254, s11, 21
	s_add_u32 s14, s40, 0x4200
	v_writelane_b32 v254, s0, 22
	s_addc_u32 s15, s41, 0
	v_writelane_b32 v254, s14, 23
	s_waitcnt lgkmcnt(0)
	v_cvt_f32_ubyte0_e32 v0, s10
	v_rcp_iflag_f32_e32 v1, v0
	v_writelane_b32 v254, s15, 24
	s_add_u32 s14, s40, 0x7400
	s_addc_u32 s15, s41, 0
	v_writelane_b32 v254, s14, 25
	v_cvt_f32_ubyte0_e32 v2, s9
	v_mul_f32_e32 v1, v2, v1
	v_writelane_b32 v254, s15, 26
	s_add_u32 s14, s40, 0x7500
	s_addc_u32 s15, s41, 0
	v_writelane_b32 v254, s14, 27
	s_add_u32 s0, s40, 0x2000
	v_trunc_f32_e32 v1, v1
	v_writelane_b32 v254, s15, 28
	v_writelane_b32 v254, s0, 29
	s_addc_u32 s0, s41, 0
	s_cmpk_lt_i32 s2, 0xc0
	v_writelane_b32 v254, s0, 30
	s_cselect_b64 s[14:15], -1, 0
	v_writelane_b32 v254, s14, 31
	s_cmp_lt_i32 s13, 0
	v_cvt_u32_f32_e32 v3, v1
	v_writelane_b32 v254, s15, 32
	s_cselect_b64 s[14:15], -1, 0
	v_writelane_b32 v254, s14, 33
	s_cmpk_lt_u32 s13, 0x6c
	v_fma_f32 v1, -v1, v0, v2
	v_writelane_b32 v254, s15, 34
	s_cselect_b64 s[14:15], -1, 0
	v_writelane_b32 v254, s14, 35
	s_add_u32 s0, s40, 0x400000
	s_mov_b32 s97, 0
	v_writelane_b32 v254, s15, 36
	v_writelane_b32 v254, s0, 37
	s_addc_u32 s0, s41, 0
	v_writelane_b32 v254, s0, 38
	s_add_u32 s0, s40, 0x300000
	v_writelane_b32 v254, s0, 39
	s_addc_u32 s0, s41, 0
	s_cmpk_lt_i32 s2, 0x300
	v_writelane_b32 v254, s0, 40
	s_cselect_b64 s[14:15], -1, 0
	v_writelane_b32 v254, s14, 41
	s_lshl_b32 s0, s13, 3
	v_mov_b32_e32 v65, 0
	v_writelane_b32 v254, s15, 42
	v_writelane_b32 v254, s0, 43
	s_add_u32 s0, s40, 0x4600000
	v_writelane_b32 v254, s0, 44
	s_addc_u32 s0, s41, 0
	v_writelane_b32 v254, s0, 45
	s_add_u32 s0, s40, 0x2600000
	v_writelane_b32 v254, s0, 46
	s_addc_u32 s0, s41, 0
	v_writelane_b32 v254, s0, 47
	s_add_u32 s0, s40, 0x1e00000
	v_writelane_b32 v254, s0, 48
	s_addc_u32 s0, s41, 0
	v_writelane_b32 v254, s0, 49
	s_add_u32 s0, s40, 0x800000
	v_writelane_b32 v254, s0, 50
	s_addc_u32 s0, s41, 0
	v_writelane_b32 v254, s0, 51
	s_add_i32 s0, s2, 0xfffffe00
	s_cmp_gt_u32 s0, 0xffffff5f
	s_mul_i32 s0, s1, s6
	s_cselect_b64 s[14:15], -1, 0
	s_add_i32 s0, s0, s4
	s_ashr_i32 s5, s0, 31
	s_lshr_b32 s5, s5, 27
	s_add_i32 s5, s0, s5
	s_ashr_i32 s6, s5, 5
	s_and_b32 s5, s5, 0xffe0
	s_sub_i32 s5, s0, s5
	s_bfe_i32 s0, s5, 0x80000
	s_bfe_u32 s0, s0, 0x3000c
	s_add_i32 s11, s5, s0
	s_mul_i32 s1, s1, s7
	s_bfe_i32 s0, s11, 0x80000
	s_and_b32 s11, s11, 0xf8
	s_add_i32 s1, s1, s4
	s_sub_i32 s5, s5, s11
	s_ashr_i32 s4, s1, 31
	v_writelane_b32 v254, s14, 52
	s_lshl_b32 s6, s6, 3
	s_sext_i32_i16 s12, s0
	s_sext_i32_i8 s5, s5
	s_lshr_b32 s4, s4, 25
	v_writelane_b32 v254, s15, 53
	s_add_i32 s14, s6, s5
	s_ashr_i32 s5, s12, 3
	s_add_i32 s4, s1, s4
	v_writelane_b32 v254, s5, 54
	s_ashr_i32 s5, s4, 7
	s_and_b32 s4, s4, 0xff80
	s_sub_i32 s1, s1, s4
	s_bfe_i32 s4, s1, 0x80000
	s_bfe_u32 s4, s4, 0x3000c
	s_add_i32 s6, s1, s4
	s_bfe_i32 s4, s6, 0x80000
	s_and_b32 s6, s6, 0xf8
	s_sub_i32 s1, s1, s6
	s_lshl_b32 s5, s5, 3
	s_sext_i32_i16 s7, s4
	s_sext_i32_i8 s1, s1
	s_add_i32 s16, s5, s1
	s_ashr_i32 s1, s7, 3
	v_writelane_b32 v254, s1, 55
	s_mov_b32 s6, s16
	s_lshr_b32 s4, s7, 3
	s_ashr_i32 s17, s16, 31
	v_writelane_b32 v254, s6, 56
	s_bfe_i64 s[4:5], s[4:5], 0x100000
	s_lshl_b64 s[4:5], s[4:5], 19
	v_writelane_b32 v254, s7, 57
	s_lshl_b64 s[6:7], s[16:17], 19
	v_writelane_b32 v254, s6, 58
	s_ashr_i32 s15, s14, 31
	s_lshr_b32 s0, s12, 3
	v_writelane_b32 v254, s7, 59
	v_writelane_b32 v254, s4, 60
	s_bfe_i64 s[0:1], s[0:1], 0x100000
	v_mov_b32_e32 v229, 0x358637bd
	v_writelane_b32 v254, s5, 61
	s_lshl_b64 s[4:5], s[14:15], 19
	v_writelane_b32 v254, s4, 62
	v_mov_b32_e32 v230, 1
	v_mov_b32_e32 v190, 0x3f4ccccd
	v_writelane_b32 v254, s5, 63
	s_lshl_b64 s[4:5], s[0:1], 19
	v_writelane_b32 v255, s4, 0
	s_lshl_b64 s[0:1], s[0:1], 21
	v_mov_b32_e32 v231, 0x1000
	v_writelane_b32 v255, s5, 1
	s_mov_b32 s4, s14
	v_writelane_b32 v255, s4, 2
	v_mov_b32_e32 v232, 0x3ecc95a3
	v_mov_b32_e32 v233, 0x3c088889
	v_writelane_b32 v255, s5, 3
	s_lshl_b64 s[4:5], s[14:15], 21
	v_writelane_b32 v255, s4, 4
	v_mov_b32_e32 v234, 0x7f800000
	v_mov_b32_e32 v235, 0x7fc00000
	v_writelane_b32 v255, s5, 5
	v_writelane_b32 v255, s0, 6
	v_readfirstlane_b32 s4, v3
	v_mov_b32_e32 v236, 0xff800000
	v_writelane_b32 v255, s1, 7
	v_cmp_ge_f32_e64 s[0:1], |v1|, v0
	s_cmp_lg_u64 s[0:1], 0
	s_addc_u32 s0, s4, 0
	s_mul_i32 s1, s0, s10
	s_sub_i32 s1, s9, s1
	s_add_i32 s1, s1, s8
	s_and_b32 s1, s1, 0xff
	s_and_b32 s4, s0, 0xff
	s_cmp_gt_u32 s4, 7
	v_writelane_b32 v255, s1, 8
	s_cselect_b64 s[0:1], -1, 0
	s_cmp_lg_u64 s[0:1], 0
	s_addc_u32 s0, s4, 0
	s_load_dwordx8 s[4:11], s[80:81], 0xd0
	v_writelane_b32 v255, s0, 9
	v_writelane_b32 v255, s13, 10
	s_lshl_b32 s0, s13, 6
	v_writelane_b32 v255, s0, 11
	s_addk_i32 s0, 0xf500
	s_lshl_b32 s79, s63, 6
	s_waitcnt lgkmcnt(0)
	s_mov_b64 s[4:5], s[8:9]
	v_writelane_b32 v255, s0, 12
	s_add_u32 s0, s4, 0x1000000
	s_addc_u32 s1, s5, 0
	v_writelane_b32 v255, s0, 13
	v_mov_b32_e32 v237, 0x3e800000
	v_bfrev_b32_e32 v238, 0.5
	v_writelane_b32 v255, s1, 14
	s_load_dwordx2 s[0:1], s[80:81], 0x68
	v_mov_b64_e32 v[192:193], 0xc0
	v_mov_b64_e32 v[194:195], 0xbf
	v_not_b32_e32 v239, 30
	s_mov_b32 s55, 0x800000
	s_waitcnt lgkmcnt(0)
	s_add_u32 s0, s0, 0xb00000
	s_addc_u32 s1, s1, 0
	v_writelane_b32 v255, s0, 15
	s_movk_i32 s92, 0x3ff
	s_movk_i32 s93, 0x1600
	v_writelane_b32 v255, s1, 16
	s_add_i32 s0, 0, 0x20020
	v_writelane_b32 v255, s0, 17
	s_add_i32 s0, 0, 0x20024
	v_writelane_b32 v255, s0, 18
	s_add_i32 s0, 0, 0x12200
	v_writelane_b32 v255, s0, 19
	s_add_i32 s0, 0, 0x15800
	v_writelane_b32 v255, s0, 20
	s_brev_b32 s0, 1
	v_writelane_b32 v255, s0, 21
	s_movk_i32 s94, 0x90
	s_movk_i32 s95, 0xf7
	v_writelane_b32 v255, s1, 22
	v_writelane_b32 v255, s2, 23
	v_writelane_b32 v255, s3, 24
	v_writelane_b32 v255, s80, 25
	s_movk_i32 s46, 0x7d0
	s_add_i32 s47, 0, 0x20000
	v_writelane_b32 v255, s81, 26
	v_writelane_b32 v255, s63, 27
	v_writelane_b32 v255, s79, 28
	s_mov_b32 s52, 0x41000000
	s_movk_i32 s54, 0xfeff
	s_mov_b32 s64, 0xc800
	s_mov_b32 s65, 0xbe800000
	s_movk_i32 s78, 0x2c00
	s_mov_b64 s[28:29], 0
	s_mov_b64 s[30:31], 0x80
	s_mov_b64 s[72:73], 0
	s_mov_b32 s74, s97
	s_and_b32 s58, s2, 7
	s_lshr_b32 s59, s2, 3
	s_mul_i32 s60, s59, 43
	s_lshr_b32 s60, s60, 8
	s_mul_i32 s61, s60, 6
	s_sub_i32 s59, s59, s61
	s_mul_i32 s58, s58, 6
	s_add_i32 s58, s58, s59
	s_mov_b32 s61, 0
	v_writelane_b32 v254, s60, 54
	v_writelane_b32 v254, s60, 55
	v_writelane_b32 v254, s58, 56
	v_writelane_b32 v254, s61, 57
	v_writelane_b32 v255, s58, 2
	v_writelane_b32 v255, s61, 3
	v_writelane_b32 v254, s61, 59
	v_writelane_b32 v254, s61, 61
	v_writelane_b32 v254, s61, 63
	v_writelane_b32 v255, s61, 1
	v_writelane_b32 v255, s61, 5
	v_writelane_b32 v255, s61, 7
	s_lshl_b32 s59, s58, 19
	v_writelane_b32 v254, s59, 58
	v_writelane_b32 v254, s59, 62
	s_lshl_b32 s59, s58, 21
	v_writelane_b32 v255, s59, 4
	s_lshl_b32 s59, s60, 19
	v_writelane_b32 v254, s59, 60
	v_writelane_b32 v255, s59, 0
	s_lshl_b32 s59, s60, 21
	v_writelane_b32 v255, s59, 6
	v_writelane_b32 v255, s33, 29
	s_barrier
	s_mov_b64 s[6:7], s[10:11]
	s_branch .LBB0_455
